# speedup vs baseline: 1.0194x; 1.0007x over previous
; #define SCHEDB() __builtin_amdgcn_sched_barrier(0)
; DEVI void gemm_residual(const bfr* W, const bfr* X, int K, float* out, char* shm, const float* xp = nullptr, const float* xs = nullptr) {
;   gemm8_linear(W, 8, X, 128, K, shm, [&](f32x4 (&acc)[2][2][4][2], int pa, int pb) { EPI8_COORDS;
; #pragma unroll
;     for (int ai = 0; ai < 2; ++ai)
; #pragma unroll
;       for (int bj = 0; bj < 2; ++bj) {
; #pragma unroll
;         for (int n = 0; n < 2; ++n)
; #pragma unroll
;           for (int m = 0; m < 4; m += 2) {
;             const int tk = pb * 256 + bj * 128 + e_wc * 32 + n * 16 + e_fr;
;             const int fi = pa * 256 + ai * 128 + e_wr * 64 + (m + (e_fq & 1)) * 16 + (e_fq >> 1) * 8;
;             f32x4* d = reinterpret_cast<f32x4*>(out + (long)tk * DM + fi);
;             const f32x4* sp = xp ? reinterpret_cast<const f32x4*>((tk < 16384 ? xp + (long)tk * DM : xs + (long)(tk - 16384) * DM) + fi) : d;
;             f32x4 o0 = sp[0], o1 = sp[1];
;             const f32x4 va = acc[ai][bj][m][n], vb2 = acc[ai][bj][m + 1][n];
; #pragma unroll
;             for (int e = 0; e < 4; ++e) { auto rr = __builtin_amdgcn_permlane16_swap(__float_as_uint(va[e]), __float_as_uint(vb2[e]), false, false);
;               o0[e] += __uint_as_float(rr[0]); o1[e] += __uint_as_float(rr[1]); }
;             d[0] = o0; d[1] = o1; }
;         SCHEDB(); } });
.LBB0_58:
	v_mov_b32_e32 v128, v164
	v_lshrrev_b32_e32 v130, 1, v128
	v_and_b32_e32 v129, 15, v128
	v_and_b32_e32 v130, 0x60, v130
	v_or3_b32 v130, v129, v130, s10
	v_ashrrev_i32_e32 v129, 2, v128
	v_and_b32_e32 v129, 0xffffffc0, v129
	v_lshrrev_b32_e32 v131, 2, v128
	v_and_or_b32 v128, v128, 16, s8
	v_add_u32_e32 v128, v128, v129
	v_and_or_b32 v128, v131, 8, v128
	v_ashrrev_i32_e32 v131, 31, v130
	v_readlane_b32 s8, v255, 2
	v_lshlrev_b64 v[132:133], 13, v[130:131]
	v_readlane_b32 s10, v255, 4
	v_readlane_b32 s11, v255, 5
	v_ashrrev_i32_e32 v129, 31, v128
	v_lshl_add_u64 v[134:135], s[10:11], 0, v[132:133]
	v_lshlrev_b64 v[132:133], 2, v[128:129]
	v_lshl_add_u64 v[128:129], v[134:135], 0, v[132:133]
	v_readlane_b32 s9, v255, 3
	s_nop 1
	v_or_b32_e32 v244, 16, v130
	v_ashrrev_i32_e32 v245, 31, v244
	v_lshlrev_b64 v[244:245], 13, v[244:245]
	v_lshl_add_u64 v[244:245], s[10:11], 0, v[244:245]
	v_lshl_add_u64 v[244:245], v[244:245], 0, v[132:133]
	v_or_b32_e32 v246, 0x80, v130
	v_ashrrev_i32_e32 v247, 31, v246
	v_lshlrev_b64 v[246:247], 13, v[246:247]
	v_lshl_add_u64 v[246:247], s[10:11], 0, v[246:247]
	v_lshl_add_u64 v[246:247], v[246:247], 0, v[132:133]
	v_or_b32_e32 v248, 0x90, v130
	v_ashrrev_i32_e32 v249, 31, v248
	v_lshlrev_b64 v[248:249], 13, v[248:249]
	v_lshl_add_u64 v[248:249], s[10:11], 0, v[248:249]
	v_lshl_add_u64 v[248:249], v[248:249], 0, v[132:133]
	global_load_dwordx4 v[196:199], v[128:129], off offset:16
	global_load_dwordx4 v[200:203], v[128:129], off
	global_load_dwordx4 v[204:207], v[128:129], off offset:144
	global_load_dwordx4 v[208:211], v[128:129], off offset:128
	global_load_dwordx4 v[212:215], v[244:245], off offset:16
	global_load_dwordx4 v[216:219], v[244:245], off
	global_load_dwordx4 v[220:223], v[244:245], off offset:144
	global_load_dwordx4 v[224:227], v[244:245], off offset:128
	global_load_dwordx4 v[228:231], v[246:247], off offset:16
	global_load_dwordx4 v[232:235], v[246:247], off
	global_load_dwordx4 v[236:239], v[246:247], off offset:144
	global_load_dwordx4 v[240:243], v[246:247], off offset:128
	global_load_dwordx4 v[174:177], v[248:249], off offset:16
	global_load_dwordx4 v[178:181], v[248:249], off
	global_load_dwordx4 v[182:185], v[248:249], off offset:144
	global_load_dwordx4 v[186:189], v[248:249], off offset:128
	v_permlane16_swap_b32_e32 v120, v124
	v_permlane16_swap_b32_e32 v121, v125
	v_permlane16_swap_b32_e32 v122, v126
	v_permlane16_swap_b32_e32 v123, v127
	v_permlane16_swap_b32_e32 v112, v116
	v_permlane16_swap_b32_e32 v113, v117
	v_permlane16_swap_b32_e32 v114, v118
	v_permlane16_swap_b32_e32 v115, v119
	v_permlane16_swap_b32_e32 v104, v108
	v_permlane16_swap_b32_e32 v105, v109
	v_permlane16_swap_b32_e32 v106, v110
	v_permlane16_swap_b32_e32 v107, v111
	v_permlane16_swap_b32_e32 v100, v96
	v_permlane16_swap_b32_e32 v101, v97
	v_permlane16_swap_b32_e32 v102, v98
	v_permlane16_swap_b32_e32 v103, v99
	v_permlane16_swap_b32_e32 v88, v92
	v_permlane16_swap_b32_e32 v89, v93
	v_permlane16_swap_b32_e32 v90, v94
	v_permlane16_swap_b32_e32 v91, v95
	v_permlane16_swap_b32_e32 v80, v84
	v_permlane16_swap_b32_e32 v81, v85
	v_permlane16_swap_b32_e32 v82, v86
	v_permlane16_swap_b32_e32 v83, v87
	v_permlane16_swap_b32_e32 v72, v76
	v_permlane16_swap_b32_e32 v73, v77
	v_permlane16_swap_b32_e32 v74, v78
	v_permlane16_swap_b32_e32 v75, v79
	v_permlane16_swap_b32_e32 v68, v64
	v_permlane16_swap_b32_e32 v69, v65
	v_permlane16_swap_b32_e32 v70, v66
	v_permlane16_swap_b32_e32 v71, v67
	v_permlane16_swap_b32_e32 v56, v60
	v_permlane16_swap_b32_e32 v57, v61
	v_permlane16_swap_b32_e32 v58, v62
	v_permlane16_swap_b32_e32 v59, v63
	v_permlane16_swap_b32_e32 v48, v52
	v_permlane16_swap_b32_e32 v49, v53
	v_permlane16_swap_b32_e32 v50, v54
	v_permlane16_swap_b32_e32 v51, v55
	v_permlane16_swap_b32_e32 v40, v44
	v_permlane16_swap_b32_e32 v41, v45
	v_permlane16_swap_b32_e32 v42, v46
	v_permlane16_swap_b32_e32 v43, v47
	v_permlane16_swap_b32_e32 v36, v32
	v_permlane16_swap_b32_e32 v37, v33
	v_permlane16_swap_b32_e32 v38, v34
	v_permlane16_swap_b32_e32 v39, v35
	v_permlane16_swap_b32_e32 v24, v28
	v_permlane16_swap_b32_e32 v25, v29
	v_permlane16_swap_b32_e32 v26, v30
	v_permlane16_swap_b32_e32 v27, v31
	v_permlane16_swap_b32_e32 v16, v20
	v_permlane16_swap_b32_e32 v17, v21
	v_permlane16_swap_b32_e32 v18, v22
	v_permlane16_swap_b32_e32 v19, v23
	v_permlane16_swap_b32_e32 v8, v12
	v_permlane16_swap_b32_e32 v9, v13
	v_permlane16_swap_b32_e32 v10, v14
	v_permlane16_swap_b32_e32 v11, v15
	v_permlane16_swap_b32_e32 v4, v0
	v_permlane16_swap_b32_e32 v5, v1
	v_permlane16_swap_b32_e32 v6, v2
	v_permlane16_swap_b32_e32 v7, v3
	s_waitcnt vmcnt(14)
	v_pk_add_f32 v[126:127], v[198:199], v[126:127]
	v_pk_add_f32 v[122:123], v[202:203], v[122:123]
	v_pk_add_f32 v[120:121], v[200:201], v[120:121]
	v_pk_add_f32 v[124:125], v[196:197], v[124:125]
	global_store_dwordx4 v[128:129], v[120:123], off
	global_store_dwordx4 v[128:129], v[124:127], off offset:16
	global_load_dwordx4 v[196:199], v[128:129], off offset:528
	global_load_dwordx4 v[200:203], v[128:129], off offset:512
	s_waitcnt vmcnt(16)
	v_pk_add_f32 v[118:119], v[206:207], v[118:119]
	v_pk_add_f32 v[114:115], v[210:211], v[114:115]
	v_pk_add_f32 v[112:113], v[208:209], v[112:113]
	v_pk_add_f32 v[116:117], v[204:205], v[116:117]
	global_store_dwordx4 v[128:129], v[112:115], off offset:128
	global_store_dwordx4 v[128:129], v[116:119], off offset:144
	global_load_dwordx4 v[204:207], v[128:129], off offset:656
	global_load_dwordx4 v[208:211], v[128:129], off offset:640
	s_waitcnt vmcnt(18)
; #define SCHEDB() __builtin_amdgcn_sched_barrier(0)
; DEVI void gemm_residual(const bfr* W, const bfr* X, int K, float* out, char* shm, const float* xp = nullptr, const float* xs = nullptr) {
;   gemm8_linear(W, 8, X, 128, K, shm, [&](f32x4 (&acc)[2][2][4][2], int pa, int pb) { EPI8_COORDS;
; #pragma unroll
;     for (int ai = 0; ai < 2; ++ai)
; #pragma unroll
;       for (int bj = 0; bj < 2; ++bj) {
; #pragma unroll
;         for (int n = 0; n < 2; ++n)
; #pragma unroll
;           for (int m = 0; m < 4; m += 2) {
;             const int tk = pb * 256 + bj * 128 + e_wc * 32 + n * 16 + e_fr;
;             const int fi = pa * 256 + ai * 128 + e_wr * 64 + (m + (e_fq & 1)) * 16 + (e_fq >> 1) * 8;
;             f32x4* d = reinterpret_cast<f32x4*>(out + (long)tk * DM + fi);
;             const f32x4* sp = xp ? reinterpret_cast<const f32x4*>((tk < 16384 ? xp + (long)tk * DM : xs + (long)(tk - 16384) * DM) + fi) : d;
;             f32x4 o0 = sp[0], o1 = sp[1];
;             const f32x4 va = acc[ai][bj][m][n], vb2 = acc[ai][bj][m + 1][n];
; #pragma unroll
;             for (int e = 0; e < 4; ++e) { auto rr = __builtin_amdgcn_permlane16_swap(__float_as_uint(va[e]), __float_as_uint(vb2[e]), false, false);
;               o0[e] += __uint_as_float(rr[0]); o1[e] += __uint_as_float(rr[1]); }
;             d[0] = o0; d[1] = o1; }
;         SCHEDB(); } });
	v_pk_add_f32 v[110:111], v[214:215], v[110:111]
	v_pk_add_f32 v[106:107], v[218:219], v[106:107]
	v_pk_add_f32 v[104:105], v[216:217], v[104:105]
	v_pk_add_f32 v[108:109], v[212:213], v[108:109]
	global_store_dwordx4 v[244:245], v[104:107], off
	global_store_dwordx4 v[244:245], v[108:111], off offset:16
	global_load_dwordx4 v[212:215], v[244:245], off offset:528
	global_load_dwordx4 v[216:219], v[244:245], off offset:512
	s_waitcnt vmcnt(20)
	v_pk_add_f32 v[98:99], v[222:223], v[98:99]
	v_pk_add_f32 v[102:103], v[226:227], v[102:103]
	v_pk_add_f32 v[100:101], v[224:225], v[100:101]
	v_pk_add_f32 v[96:97], v[220:221], v[96:97]
	global_store_dwordx4 v[244:245], v[100:103], off offset:128
	global_store_dwordx4 v[244:245], v[96:99], off offset:144
	global_load_dwordx4 v[220:223], v[244:245], off offset:656
	global_load_dwordx4 v[224:227], v[244:245], off offset:640
	s_waitcnt vmcnt(22)
	v_pk_add_f32 v[94:95], v[230:231], v[94:95]
	v_pk_add_f32 v[90:91], v[234:235], v[90:91]
	v_pk_add_f32 v[88:89], v[232:233], v[88:89]
	v_pk_add_f32 v[92:93], v[228:229], v[92:93]
	global_store_dwordx4 v[246:247], v[88:91], off
	global_store_dwordx4 v[246:247], v[92:95], off offset:16
	global_load_dwordx4 v[228:231], v[246:247], off offset:528
	global_load_dwordx4 v[232:235], v[246:247], off offset:512
	s_waitcnt vmcnt(24)
	v_pk_add_f32 v[86:87], v[238:239], v[86:87]
	v_pk_add_f32 v[82:83], v[242:243], v[82:83]
	v_pk_add_f32 v[80:81], v[240:241], v[80:81]
	v_pk_add_f32 v[84:85], v[236:237], v[84:85]
	global_store_dwordx4 v[246:247], v[80:83], off offset:128
	global_store_dwordx4 v[246:247], v[84:87], off offset:144
	global_load_dwordx4 v[236:239], v[246:247], off offset:656
	global_load_dwordx4 v[240:243], v[246:247], off offset:640
	s_waitcnt vmcnt(26)
	v_pk_add_f32 v[78:79], v[176:177], v[78:79]
	v_pk_add_f32 v[74:75], v[180:181], v[74:75]
	v_pk_add_f32 v[72:73], v[178:179], v[72:73]
	v_pk_add_f32 v[76:77], v[174:175], v[76:77]
	global_store_dwordx4 v[248:249], v[72:75], off
	global_store_dwordx4 v[248:249], v[76:79], off offset:16
	global_load_dwordx4 v[174:177], v[248:249], off offset:528
	global_load_dwordx4 v[178:181], v[248:249], off offset:512
	s_waitcnt vmcnt(28)
	v_pk_add_f32 v[66:67], v[184:185], v[66:67]
	v_pk_add_f32 v[70:71], v[188:189], v[70:71]
	v_pk_add_f32 v[68:69], v[186:187], v[68:69]
	v_pk_add_f32 v[64:65], v[182:183], v[64:65]
	global_store_dwordx4 v[248:249], v[68:71], off offset:128
	global_store_dwordx4 v[248:249], v[64:67], off offset:144
	global_load_dwordx4 v[182:185], v[248:249], off offset:656
	global_load_dwordx4 v[186:189], v[248:249], off offset:640
	s_waitcnt vmcnt(28)
	v_pk_add_f32 v[62:63], v[198:199], v[62:63]
	v_pk_add_f32 v[58:59], v[202:203], v[58:59]
	v_pk_add_f32 v[56:57], v[200:201], v[56:57]
	v_pk_add_f32 v[60:61], v[196:197], v[60:61]
	global_store_dwordx4 v[128:129], v[56:59], off offset:512
	global_store_dwordx4 v[128:129], v[60:63], off offset:528
	s_waitcnt vmcnt(26)
	v_pk_add_f32 v[54:55], v[206:207], v[54:55]
	v_pk_add_f32 v[50:51], v[210:211], v[50:51]
	v_pk_add_f32 v[48:49], v[208:209], v[48:49]
	v_pk_add_f32 v[52:53], v[204:205], v[52:53]
	global_store_dwordx4 v[128:129], v[48:51], off offset:640
	global_store_dwordx4 v[128:129], v[52:55], off offset:656
	s_waitcnt vmcnt(24)
	v_pk_add_f32 v[46:47], v[214:215], v[46:47]
	v_pk_add_f32 v[42:43], v[218:219], v[42:43]
	v_pk_add_f32 v[40:41], v[216:217], v[40:41]
	v_pk_add_f32 v[44:45], v[212:213], v[44:45]
	global_store_dwordx4 v[244:245], v[40:43], off offset:512
	global_store_dwordx4 v[244:245], v[44:47], off offset:528
	s_waitcnt vmcnt(22)
	v_pk_add_f32 v[34:35], v[222:223], v[34:35]
	v_pk_add_f32 v[38:39], v[226:227], v[38:39]
	v_pk_add_f32 v[36:37], v[224:225], v[36:37]
	v_pk_add_f32 v[32:33], v[220:221], v[32:33]
	global_store_dwordx4 v[244:245], v[36:39], off offset:640
	global_store_dwordx4 v[244:245], v[32:35], off offset:656
	s_waitcnt vmcnt(20)
	v_pk_add_f32 v[30:31], v[230:231], v[30:31]
	v_pk_add_f32 v[26:27], v[234:235], v[26:27]
	v_pk_add_f32 v[24:25], v[232:233], v[24:25]
	v_pk_add_f32 v[28:29], v[228:229], v[28:29]
	global_store_dwordx4 v[246:247], v[24:27], off offset:512
	global_store_dwordx4 v[246:247], v[28:31], off offset:528
	s_waitcnt vmcnt(18)
	v_pk_add_f32 v[22:23], v[238:239], v[22:23]
	v_pk_add_f32 v[18:19], v[242:243], v[18:19]
	v_pk_add_f32 v[16:17], v[240:241], v[16:17]
	v_pk_add_f32 v[20:21], v[236:237], v[20:21]
	global_store_dwordx4 v[246:247], v[16:19], off offset:640
	global_store_dwordx4 v[246:247], v[20:23], off offset:656
	s_waitcnt vmcnt(16)
	v_pk_add_f32 v[14:15], v[176:177], v[14:15]
	v_pk_add_f32 v[10:11], v[180:181], v[10:11]
	v_pk_add_f32 v[8:9], v[178:179], v[8:9]
	v_pk_add_f32 v[12:13], v[174:175], v[12:13]
	global_store_dwordx4 v[248:249], v[8:11], off offset:512
	global_store_dwordx4 v[248:249], v[12:15], off offset:528
	s_waitcnt vmcnt(14)
	v_pk_add_f32 v[2:3], v[184:185], v[2:3]
	v_pk_add_f32 v[6:7], v[188:189], v[6:7]
	v_pk_add_f32 v[4:5], v[186:187], v[4:5]
	v_pk_add_f32 v[0:1], v[182:183], v[0:1]
	global_store_dwordx4 v[248:249], v[4:7], off offset:640
	global_store_dwordx4 v[248:249], v[0:3], off offset:656
	s_and_b64 vcc, exec, s[6:7]
	s_mov_b32 s9, s68
	s_mov_b32 s2, s65
	s_cbranch_vccnz .LBB0_71

; #define SCHEDB() __builtin_amdgcn_sched_barrier(0)
; DEVI void gemm_residual(const bfr* W, const bfr* X, int K, float* out, char* shm, const float* xp = nullptr, const float* xs = nullptr) {
;   gemm8_linear(W, 8, X, 128, K, shm, [&](f32x4 (&acc)[2][2][4][2], int pa, int pb) { EPI8_COORDS;
; #pragma unroll
;     for (int ai = 0; ai < 2; ++ai)
; #pragma unroll
;       for (int bj = 0; bj < 2; ++bj) {
; #pragma unroll
;         for (int n = 0; n < 2; ++n)
; #pragma unroll
;           for (int m = 0; m < 4; m += 2) {
;             const int tk = pb * 256 + bj * 128 + e_wc * 32 + n * 16 + e_fr;
;             const int fi = pa * 256 + ai * 128 + e_wr * 64 + (m + (e_fq & 1)) * 16 + (e_fq >> 1) * 8;
;             f32x4* d = reinterpret_cast<f32x4*>(out + (long)tk * DM + fi);
;             const f32x4* sp = xp ? reinterpret_cast<const f32x4*>((tk < 16384 ? xp + (long)tk * DM : xs + (long)(tk - 16384) * DM) + fi) : d;
;             f32x4 o0 = sp[0], o1 = sp[1];
;             const f32x4 va = acc[ai][bj][m][n], vb2 = acc[ai][bj][m + 1][n];
; #pragma unroll
;             for (int e = 0; e < 4; ++e) { auto rr = __builtin_amdgcn_permlane16_swap(__float_as_uint(va[e]), __float_as_uint(vb2[e]), false, false);
;               o0[e] += __uint_as_float(rr[0]); o1[e] += __uint_as_float(rr[1]); }
;             d[0] = o0; d[1] = o1; }
;         SCHEDB(); } });
.LBB0_278:
	v_mov_b32_e32 v128, v164
	v_lshrrev_b32_e32 v130, 1, v128
	v_and_b32_e32 v129, 15, v128
	v_and_b32_e32 v130, 0x60, v130
	v_or3_b32 v130, v129, v130, s10
	v_ashrrev_i32_e32 v129, 2, v128
	v_and_b32_e32 v129, 0xffffffc0, v129
	v_lshrrev_b32_e32 v131, 2, v128
	v_and_or_b32 v128, v128, 16, s8
	v_add_u32_e32 v128, v128, v129
	v_and_or_b32 v128, v131, 8, v128
	v_ashrrev_i32_e32 v131, 31, v130
	v_readlane_b32 s8, v255, 2
	v_lshlrev_b64 v[132:133], 13, v[130:131]
	v_readlane_b32 s10, v255, 4
	v_readlane_b32 s11, v255, 5
	v_ashrrev_i32_e32 v129, 31, v128
	v_lshl_add_u64 v[134:135], s[10:11], 0, v[132:133]
	v_lshlrev_b64 v[132:133], 2, v[128:129]
	v_lshl_add_u64 v[128:129], v[134:135], 0, v[132:133]
	v_readlane_b32 s9, v255, 3
	s_nop 1
	v_or_b32_e32 v244, 16, v130
	v_ashrrev_i32_e32 v245, 31, v244
	v_lshlrev_b64 v[244:245], 13, v[244:245]
	v_lshl_add_u64 v[244:245], s[10:11], 0, v[244:245]
	v_lshl_add_u64 v[244:245], v[244:245], 0, v[132:133]
	v_or_b32_e32 v246, 0x80, v130
	v_ashrrev_i32_e32 v247, 31, v246
	v_lshlrev_b64 v[246:247], 13, v[246:247]
	v_lshl_add_u64 v[246:247], s[10:11], 0, v[246:247]
	v_lshl_add_u64 v[246:247], v[246:247], 0, v[132:133]
	v_or_b32_e32 v248, 0x90, v130
	v_ashrrev_i32_e32 v249, 31, v248
	v_lshlrev_b64 v[248:249], 13, v[248:249]
	v_lshl_add_u64 v[248:249], s[10:11], 0, v[248:249]
	v_lshl_add_u64 v[248:249], v[248:249], 0, v[132:133]
	global_load_dwordx4 v[196:199], v[128:129], off offset:16
	global_load_dwordx4 v[200:203], v[128:129], off
	global_load_dwordx4 v[204:207], v[128:129], off offset:144
	global_load_dwordx4 v[208:211], v[128:129], off offset:128
	global_load_dwordx4 v[212:215], v[244:245], off offset:16
	global_load_dwordx4 v[216:219], v[244:245], off
	global_load_dwordx4 v[220:223], v[244:245], off offset:144
	global_load_dwordx4 v[224:227], v[244:245], off offset:128
	global_load_dwordx4 v[228:231], v[246:247], off offset:16
	global_load_dwordx4 v[232:235], v[246:247], off
	global_load_dwordx4 v[236:239], v[246:247], off offset:144
	global_load_dwordx4 v[240:243], v[246:247], off offset:128
	global_load_dwordx4 v[174:177], v[248:249], off offset:16
	global_load_dwordx4 v[178:181], v[248:249], off
	global_load_dwordx4 v[182:185], v[248:249], off offset:144
	global_load_dwordx4 v[186:189], v[248:249], off offset:128
	v_permlane16_swap_b32_e32 v120, v124
	v_permlane16_swap_b32_e32 v121, v125
	v_permlane16_swap_b32_e32 v122, v126
	v_permlane16_swap_b32_e32 v123, v127
	v_permlane16_swap_b32_e32 v112, v116
	v_permlane16_swap_b32_e32 v113, v117
	v_permlane16_swap_b32_e32 v114, v118
	v_permlane16_swap_b32_e32 v115, v119
	v_permlane16_swap_b32_e32 v104, v108
	v_permlane16_swap_b32_e32 v105, v109
	v_permlane16_swap_b32_e32 v106, v110
	v_permlane16_swap_b32_e32 v107, v111
	v_permlane16_swap_b32_e32 v100, v96
	v_permlane16_swap_b32_e32 v101, v97
	v_permlane16_swap_b32_e32 v102, v98
	v_permlane16_swap_b32_e32 v103, v99
	v_permlane16_swap_b32_e32 v88, v92
	v_permlane16_swap_b32_e32 v89, v93
	v_permlane16_swap_b32_e32 v90, v94
	v_permlane16_swap_b32_e32 v91, v95
	v_permlane16_swap_b32_e32 v80, v84
	v_permlane16_swap_b32_e32 v81, v85
	v_permlane16_swap_b32_e32 v82, v86
	v_permlane16_swap_b32_e32 v83, v87
	v_permlane16_swap_b32_e32 v72, v76
	v_permlane16_swap_b32_e32 v73, v77
	v_permlane16_swap_b32_e32 v74, v78
	v_permlane16_swap_b32_e32 v75, v79
	v_permlane16_swap_b32_e32 v68, v64
	v_permlane16_swap_b32_e32 v69, v65
	v_permlane16_swap_b32_e32 v70, v66
	v_permlane16_swap_b32_e32 v71, v67
	v_permlane16_swap_b32_e32 v56, v60
	v_permlane16_swap_b32_e32 v57, v61
	v_permlane16_swap_b32_e32 v58, v62
	v_permlane16_swap_b32_e32 v59, v63
	v_permlane16_swap_b32_e32 v48, v52
	v_permlane16_swap_b32_e32 v49, v53
	v_permlane16_swap_b32_e32 v50, v54
	v_permlane16_swap_b32_e32 v51, v55
	v_permlane16_swap_b32_e32 v40, v44
	v_permlane16_swap_b32_e32 v41, v45
	v_permlane16_swap_b32_e32 v42, v46
	v_permlane16_swap_b32_e32 v43, v47
	v_permlane16_swap_b32_e32 v36, v32
	v_permlane16_swap_b32_e32 v37, v33
	v_permlane16_swap_b32_e32 v38, v34
	v_permlane16_swap_b32_e32 v39, v35
	v_permlane16_swap_b32_e32 v24, v28
	v_permlane16_swap_b32_e32 v25, v29
	v_permlane16_swap_b32_e32 v26, v30
	v_permlane16_swap_b32_e32 v27, v31
	v_permlane16_swap_b32_e32 v16, v20
	v_permlane16_swap_b32_e32 v17, v21
	v_permlane16_swap_b32_e32 v18, v22
	v_permlane16_swap_b32_e32 v19, v23
	v_permlane16_swap_b32_e32 v8, v12
	v_permlane16_swap_b32_e32 v9, v13
	v_permlane16_swap_b32_e32 v10, v14
	v_permlane16_swap_b32_e32 v11, v15
	v_permlane16_swap_b32_e32 v4, v0
	v_permlane16_swap_b32_e32 v5, v1
	v_permlane16_swap_b32_e32 v6, v2
	v_permlane16_swap_b32_e32 v7, v3
	s_waitcnt vmcnt(14)
	v_pk_add_f32 v[126:127], v[198:199], v[126:127]
	v_pk_add_f32 v[122:123], v[202:203], v[122:123]
	v_pk_add_f32 v[120:121], v[200:201], v[120:121]
	v_pk_add_f32 v[124:125], v[196:197], v[124:125]
	global_store_dwordx4 v[128:129], v[120:123], off
	global_store_dwordx4 v[128:129], v[124:127], off offset:16
	global_load_dwordx4 v[196:199], v[128:129], off offset:528
	global_load_dwordx4 v[200:203], v[128:129], off offset:512
	s_waitcnt vmcnt(16)
	v_pk_add_f32 v[118:119], v[206:207], v[118:119]
	v_pk_add_f32 v[114:115], v[210:211], v[114:115]
	v_pk_add_f32 v[112:113], v[208:209], v[112:113]
	v_pk_add_f32 v[116:117], v[204:205], v[116:117]
	global_store_dwordx4 v[128:129], v[112:115], off offset:128
	global_store_dwordx4 v[128:129], v[116:119], off offset:144
	global_load_dwordx4 v[204:207], v[128:129], off offset:656
	global_load_dwordx4 v[208:211], v[128:129], off offset:640
	s_waitcnt vmcnt(18)
; #define SCHEDB() __builtin_amdgcn_sched_barrier(0)
; DEVI void gemm_residual(const bfr* W, const bfr* X, int K, float* out, char* shm, const float* xp = nullptr, const float* xs = nullptr) {
;   gemm8_linear(W, 8, X, 128, K, shm, [&](f32x4 (&acc)[2][2][4][2], int pa, int pb) { EPI8_COORDS;
; #pragma unroll
;     for (int ai = 0; ai < 2; ++ai)
; #pragma unroll
;       for (int bj = 0; bj < 2; ++bj) {
; #pragma unroll
;         for (int n = 0; n < 2; ++n)
; #pragma unroll
;           for (int m = 0; m < 4; m += 2) {
;             const int tk = pb * 256 + bj * 128 + e_wc * 32 + n * 16 + e_fr;
;             const int fi = pa * 256 + ai * 128 + e_wr * 64 + (m + (e_fq & 1)) * 16 + (e_fq >> 1) * 8;
;             f32x4* d = reinterpret_cast<f32x4*>(out + (long)tk * DM + fi);
;             const f32x4* sp = xp ? reinterpret_cast<const f32x4*>((tk < 16384 ? xp + (long)tk * DM : xs + (long)(tk - 16384) * DM) + fi) : d;
;             f32x4 o0 = sp[0], o1 = sp[1];
;             const f32x4 va = acc[ai][bj][m][n], vb2 = acc[ai][bj][m + 1][n];
; #pragma unroll
;             for (int e = 0; e < 4; ++e) { auto rr = __builtin_amdgcn_permlane16_swap(__float_as_uint(va[e]), __float_as_uint(vb2[e]), false, false);
;               o0[e] += __uint_as_float(rr[0]); o1[e] += __uint_as_float(rr[1]); }
;             d[0] = o0; d[1] = o1; }
;         SCHEDB(); } });
	v_pk_add_f32 v[110:111], v[214:215], v[110:111]
	v_pk_add_f32 v[106:107], v[218:219], v[106:107]
	v_pk_add_f32 v[104:105], v[216:217], v[104:105]
	v_pk_add_f32 v[108:109], v[212:213], v[108:109]
	global_store_dwordx4 v[244:245], v[104:107], off
	global_store_dwordx4 v[244:245], v[108:111], off offset:16
	global_load_dwordx4 v[212:215], v[244:245], off offset:528
	global_load_dwordx4 v[216:219], v[244:245], off offset:512
	s_waitcnt vmcnt(20)
	v_pk_add_f32 v[98:99], v[222:223], v[98:99]
	v_pk_add_f32 v[102:103], v[226:227], v[102:103]
	v_pk_add_f32 v[100:101], v[224:225], v[100:101]
	v_pk_add_f32 v[96:97], v[220:221], v[96:97]
	global_store_dwordx4 v[244:245], v[100:103], off offset:128
	global_store_dwordx4 v[244:245], v[96:99], off offset:144
	global_load_dwordx4 v[220:223], v[244:245], off offset:656
	global_load_dwordx4 v[224:227], v[244:245], off offset:640
	s_waitcnt vmcnt(22)
	v_pk_add_f32 v[94:95], v[230:231], v[94:95]
	v_pk_add_f32 v[90:91], v[234:235], v[90:91]
	v_pk_add_f32 v[88:89], v[232:233], v[88:89]
	v_pk_add_f32 v[92:93], v[228:229], v[92:93]
	global_store_dwordx4 v[246:247], v[88:91], off
	global_store_dwordx4 v[246:247], v[92:95], off offset:16
	global_load_dwordx4 v[228:231], v[246:247], off offset:528
	global_load_dwordx4 v[232:235], v[246:247], off offset:512
	s_waitcnt vmcnt(24)
	v_pk_add_f32 v[86:87], v[238:239], v[86:87]
	v_pk_add_f32 v[82:83], v[242:243], v[82:83]
	v_pk_add_f32 v[80:81], v[240:241], v[80:81]
	v_pk_add_f32 v[84:85], v[236:237], v[84:85]
	global_store_dwordx4 v[246:247], v[80:83], off offset:128
	global_store_dwordx4 v[246:247], v[84:87], off offset:144
	global_load_dwordx4 v[236:239], v[246:247], off offset:656
	global_load_dwordx4 v[240:243], v[246:247], off offset:640
	s_waitcnt vmcnt(26)
	v_pk_add_f32 v[78:79], v[176:177], v[78:79]
	v_pk_add_f32 v[74:75], v[180:181], v[74:75]
	v_pk_add_f32 v[72:73], v[178:179], v[72:73]
	v_pk_add_f32 v[76:77], v[174:175], v[76:77]
	global_store_dwordx4 v[248:249], v[72:75], off
	global_store_dwordx4 v[248:249], v[76:79], off offset:16
	global_load_dwordx4 v[174:177], v[248:249], off offset:528
	global_load_dwordx4 v[178:181], v[248:249], off offset:512
	s_waitcnt vmcnt(28)
	v_pk_add_f32 v[66:67], v[184:185], v[66:67]
	v_pk_add_f32 v[70:71], v[188:189], v[70:71]
	v_pk_add_f32 v[68:69], v[186:187], v[68:69]
	v_pk_add_f32 v[64:65], v[182:183], v[64:65]
	global_store_dwordx4 v[248:249], v[68:71], off offset:128
	global_store_dwordx4 v[248:249], v[64:67], off offset:144
	global_load_dwordx4 v[182:185], v[248:249], off offset:656
	global_load_dwordx4 v[186:189], v[248:249], off offset:640
	s_waitcnt vmcnt(28)
	v_pk_add_f32 v[62:63], v[198:199], v[62:63]
	v_pk_add_f32 v[58:59], v[202:203], v[58:59]
	v_pk_add_f32 v[56:57], v[200:201], v[56:57]
	v_pk_add_f32 v[60:61], v[196:197], v[60:61]
	global_store_dwordx4 v[128:129], v[56:59], off offset:512
	global_store_dwordx4 v[128:129], v[60:63], off offset:528
	s_waitcnt vmcnt(26)
	v_pk_add_f32 v[54:55], v[206:207], v[54:55]
	v_pk_add_f32 v[50:51], v[210:211], v[50:51]
	v_pk_add_f32 v[48:49], v[208:209], v[48:49]
	v_pk_add_f32 v[52:53], v[204:205], v[52:53]
	global_store_dwordx4 v[128:129], v[48:51], off offset:640
	global_store_dwordx4 v[128:129], v[52:55], off offset:656
	s_waitcnt vmcnt(24)
	v_pk_add_f32 v[46:47], v[214:215], v[46:47]
	v_pk_add_f32 v[42:43], v[218:219], v[42:43]
	v_pk_add_f32 v[40:41], v[216:217], v[40:41]
	v_pk_add_f32 v[44:45], v[212:213], v[44:45]
	global_store_dwordx4 v[244:245], v[40:43], off offset:512
	global_store_dwordx4 v[244:245], v[44:47], off offset:528
	s_waitcnt vmcnt(22)
	v_pk_add_f32 v[34:35], v[222:223], v[34:35]
	v_pk_add_f32 v[38:39], v[226:227], v[38:39]
	v_pk_add_f32 v[36:37], v[224:225], v[36:37]
	v_pk_add_f32 v[32:33], v[220:221], v[32:33]
	global_store_dwordx4 v[244:245], v[36:39], off offset:640
	global_store_dwordx4 v[244:245], v[32:35], off offset:656
	s_waitcnt vmcnt(20)
	v_pk_add_f32 v[30:31], v[230:231], v[30:31]
	v_pk_add_f32 v[26:27], v[234:235], v[26:27]
	v_pk_add_f32 v[24:25], v[232:233], v[24:25]
	v_pk_add_f32 v[28:29], v[228:229], v[28:29]
	global_store_dwordx4 v[246:247], v[24:27], off offset:512
	global_store_dwordx4 v[246:247], v[28:31], off offset:528
	s_waitcnt vmcnt(18)
	v_pk_add_f32 v[22:23], v[238:239], v[22:23]
	v_pk_add_f32 v[18:19], v[242:243], v[18:19]
	v_pk_add_f32 v[16:17], v[240:241], v[16:17]
	v_pk_add_f32 v[20:21], v[236:237], v[20:21]
	global_store_dwordx4 v[246:247], v[16:19], off offset:640
	global_store_dwordx4 v[246:247], v[20:23], off offset:656
	s_waitcnt vmcnt(16)
	v_pk_add_f32 v[14:15], v[176:177], v[14:15]
	v_pk_add_f32 v[10:11], v[180:181], v[10:11]
	v_pk_add_f32 v[8:9], v[178:179], v[8:9]
	v_pk_add_f32 v[12:13], v[174:175], v[12:13]
	global_store_dwordx4 v[248:249], v[8:11], off offset:512
	global_store_dwordx4 v[248:249], v[12:15], off offset:528
	s_waitcnt vmcnt(14)
	v_pk_add_f32 v[2:3], v[184:185], v[2:3]
	v_pk_add_f32 v[6:7], v[188:189], v[6:7]
	v_pk_add_f32 v[4:5], v[186:187], v[4:5]
	v_pk_add_f32 v[0:1], v[182:183], v[0:1]
	global_store_dwordx4 v[248:249], v[4:7], off offset:640
	global_store_dwordx4 v[248:249], v[0:3], off offset:656
	s_and_b64 vcc, exec, s[6:7]
	s_mov_b32 s9, s72
	s_mov_b32 s2, s69
	s_cbranch_vccnz .LBB0_291

; #define SCHEDB() __builtin_amdgcn_sched_barrier(0)
; DEVI void gemm_residual(const bfr* W, const bfr* X, int K, float* out, char* shm, const float* xp = nullptr, const float* xs = nullptr) {
;   gemm8_linear(W, 8, X, 128, K, shm, [&](f32x4 (&acc)[2][2][4][2], int pa, int pb) { EPI8_COORDS;
; #pragma unroll
;     for (int ai = 0; ai < 2; ++ai)
; #pragma unroll
;       for (int bj = 0; bj < 2; ++bj) {
; #pragma unroll
;         for (int n = 0; n < 2; ++n)
; #pragma unroll
;           for (int m = 0; m < 4; m += 2) {
;             const int tk = pb * 256 + bj * 128 + e_wc * 32 + n * 16 + e_fr;
;             const int fi = pa * 256 + ai * 128 + e_wr * 64 + (m + (e_fq & 1)) * 16 + (e_fq >> 1) * 8;
;             f32x4* d = reinterpret_cast<f32x4*>(out + (long)tk * DM + fi);
;             const f32x4* sp = xp ? reinterpret_cast<const f32x4*>((tk < 16384 ? xp + (long)tk * DM : xs + (long)(tk - 16384) * DM) + fi) : d;
;             f32x4 o0 = sp[0], o1 = sp[1];
;             const f32x4 va = acc[ai][bj][m][n], vb2 = acc[ai][bj][m + 1][n];
; #pragma unroll
;             for (int e = 0; e < 4; ++e) { auto rr = __builtin_amdgcn_permlane16_swap(__float_as_uint(va[e]), __float_as_uint(vb2[e]), false, false);
;               o0[e] += __uint_as_float(rr[0]); o1[e] += __uint_as_float(rr[1]); }
;             d[0] = o0; d[1] = o1; }
;         SCHEDB(); } });
.LBB0_374:
	v_mov_b32_e32 v128, v164
	v_readlane_b32 s92, v255, 2
	v_lshrrev_b32_e32 v130, 1, v128
	v_and_b32_e32 v129, 15, v128
	v_and_b32_e32 v130, 0x60, v130
	v_or3_b32 v130, v129, v130, s34
	v_ashrrev_i32_e32 v129, 2, v128
	v_and_b32_e32 v129, 0xffffffc0, v129
	v_lshrrev_b32_e32 v131, 2, v128
	v_and_or_b32 v128, v128, 16, s10
	v_add_u32_e32 v128, v128, v129
	v_and_or_b32 v128, v131, 8, v128
	v_ashrrev_i32_e32 v131, 31, v130
	v_lshlrev_b64 v[132:133], 13, v[130:131]
	v_readlane_b32 s94, v255, 4
	v_readlane_b32 s95, v255, 5
	v_ashrrev_i32_e32 v129, 31, v128
	v_lshl_add_u64 v[134:135], s[94:95], 0, v[132:133]
	v_lshlrev_b64 v[132:133], 2, v[128:129]
	v_lshl_add_u64 v[128:129], v[134:135], 0, v[132:133]
	v_readlane_b32 s93, v255, 3
	s_nop 1
	v_or_b32_e32 v244, 16, v130
	v_ashrrev_i32_e32 v245, 31, v244
	v_lshlrev_b64 v[244:245], 13, v[244:245]
	v_lshl_add_u64 v[244:245], s[94:95], 0, v[244:245]
	v_lshl_add_u64 v[244:245], v[244:245], 0, v[132:133]
	v_or_b32_e32 v246, 0x80, v130
	v_ashrrev_i32_e32 v247, 31, v246
	v_lshlrev_b64 v[246:247], 13, v[246:247]
	v_lshl_add_u64 v[246:247], s[94:95], 0, v[246:247]
	v_lshl_add_u64 v[246:247], v[246:247], 0, v[132:133]
	v_or_b32_e32 v248, 0x90, v130
	v_ashrrev_i32_e32 v249, 31, v248
	v_lshlrev_b64 v[248:249], 13, v[248:249]
	v_lshl_add_u64 v[248:249], s[94:95], 0, v[248:249]
	v_lshl_add_u64 v[248:249], v[248:249], 0, v[132:133]
	global_load_dwordx4 v[196:199], v[128:129], off offset:16
	global_load_dwordx4 v[200:203], v[128:129], off
	global_load_dwordx4 v[204:207], v[128:129], off offset:144
	global_load_dwordx4 v[208:211], v[128:129], off offset:128
	global_load_dwordx4 v[212:215], v[244:245], off offset:16
	global_load_dwordx4 v[216:219], v[244:245], off
	global_load_dwordx4 v[220:223], v[244:245], off offset:144
	global_load_dwordx4 v[224:227], v[244:245], off offset:128
	global_load_dwordx4 v[228:231], v[246:247], off offset:16
	global_load_dwordx4 v[232:235], v[246:247], off
	global_load_dwordx4 v[236:239], v[246:247], off offset:144
	global_load_dwordx4 v[240:243], v[246:247], off offset:128
	global_load_dwordx4 v[174:177], v[248:249], off offset:16
	global_load_dwordx4 v[178:181], v[248:249], off
	global_load_dwordx4 v[182:185], v[248:249], off offset:144
	global_load_dwordx4 v[186:189], v[248:249], off offset:128
	v_permlane16_swap_b32_e32 v120, v124
	v_permlane16_swap_b32_e32 v121, v125
	v_permlane16_swap_b32_e32 v122, v126
	v_permlane16_swap_b32_e32 v123, v127
	v_permlane16_swap_b32_e32 v112, v116
	v_permlane16_swap_b32_e32 v113, v117
	v_permlane16_swap_b32_e32 v114, v118
	v_permlane16_swap_b32_e32 v115, v119
	v_permlane16_swap_b32_e32 v104, v108
	v_permlane16_swap_b32_e32 v105, v109
	v_permlane16_swap_b32_e32 v106, v110
	v_permlane16_swap_b32_e32 v107, v111
	v_permlane16_swap_b32_e32 v100, v96
	v_permlane16_swap_b32_e32 v101, v97
	v_permlane16_swap_b32_e32 v102, v98
	v_permlane16_swap_b32_e32 v103, v99
	v_permlane16_swap_b32_e32 v88, v92
	v_permlane16_swap_b32_e32 v89, v93
	v_permlane16_swap_b32_e32 v90, v94
	v_permlane16_swap_b32_e32 v91, v95
	v_permlane16_swap_b32_e32 v80, v84
	v_permlane16_swap_b32_e32 v81, v85
	v_permlane16_swap_b32_e32 v82, v86
	v_permlane16_swap_b32_e32 v83, v87
	v_permlane16_swap_b32_e32 v72, v76
	v_permlane16_swap_b32_e32 v73, v77
	v_permlane16_swap_b32_e32 v74, v78
	v_permlane16_swap_b32_e32 v75, v79
	v_permlane16_swap_b32_e32 v68, v64
	v_permlane16_swap_b32_e32 v69, v65
	v_permlane16_swap_b32_e32 v70, v66
	v_permlane16_swap_b32_e32 v71, v67
	v_permlane16_swap_b32_e32 v56, v60
	v_permlane16_swap_b32_e32 v57, v61
	v_permlane16_swap_b32_e32 v58, v62
	v_permlane16_swap_b32_e32 v59, v63
	v_permlane16_swap_b32_e32 v48, v52
	v_permlane16_swap_b32_e32 v49, v53
	v_permlane16_swap_b32_e32 v50, v54
	v_permlane16_swap_b32_e32 v51, v55
	v_permlane16_swap_b32_e32 v40, v44
	v_permlane16_swap_b32_e32 v41, v45
	v_permlane16_swap_b32_e32 v42, v46
	v_permlane16_swap_b32_e32 v43, v47
	v_permlane16_swap_b32_e32 v36, v32
	v_permlane16_swap_b32_e32 v37, v33
	v_permlane16_swap_b32_e32 v38, v34
	v_permlane16_swap_b32_e32 v39, v35
	v_permlane16_swap_b32_e32 v24, v28
	v_permlane16_swap_b32_e32 v25, v29
	v_permlane16_swap_b32_e32 v26, v30
	v_permlane16_swap_b32_e32 v27, v31
	v_permlane16_swap_b32_e32 v16, v20
	v_permlane16_swap_b32_e32 v17, v21
	v_permlane16_swap_b32_e32 v18, v22
	v_permlane16_swap_b32_e32 v19, v23
	v_permlane16_swap_b32_e32 v8, v12
	v_permlane16_swap_b32_e32 v9, v13
	v_permlane16_swap_b32_e32 v10, v14
	v_permlane16_swap_b32_e32 v11, v15
	v_permlane16_swap_b32_e32 v4, v0
	v_permlane16_swap_b32_e32 v5, v1
	v_permlane16_swap_b32_e32 v6, v2
	v_permlane16_swap_b32_e32 v7, v3
	s_waitcnt vmcnt(14)
	v_pk_add_f32 v[126:127], v[198:199], v[126:127]
	v_pk_add_f32 v[122:123], v[202:203], v[122:123]
	v_pk_add_f32 v[120:121], v[200:201], v[120:121]
	v_pk_add_f32 v[124:125], v[196:197], v[124:125]
	global_store_dwordx4 v[128:129], v[120:123], off
	global_store_dwordx4 v[128:129], v[124:127], off offset:16
	global_load_dwordx4 v[196:199], v[128:129], off offset:528
	global_load_dwordx4 v[200:203], v[128:129], off offset:512
	s_waitcnt vmcnt(16)
	v_pk_add_f32 v[118:119], v[206:207], v[118:119]
	v_pk_add_f32 v[114:115], v[210:211], v[114:115]
	v_pk_add_f32 v[112:113], v[208:209], v[112:113]
	v_pk_add_f32 v[116:117], v[204:205], v[116:117]
	global_store_dwordx4 v[128:129], v[112:115], off offset:128
	global_store_dwordx4 v[128:129], v[116:119], off offset:144
	global_load_dwordx4 v[204:207], v[128:129], off offset:656
	global_load_dwordx4 v[208:211], v[128:129], off offset:640
	s_waitcnt vmcnt(18)
; #define SCHEDB() __builtin_amdgcn_sched_barrier(0)
; DEVI void gemm_residual(const bfr* W, const bfr* X, int K, float* out, char* shm, const float* xp = nullptr, const float* xs = nullptr) {
;   gemm8_linear(W, 8, X, 128, K, shm, [&](f32x4 (&acc)[2][2][4][2], int pa, int pb) { EPI8_COORDS;
; #pragma unroll
;     for (int ai = 0; ai < 2; ++ai)
; #pragma unroll
;       for (int bj = 0; bj < 2; ++bj) {
; #pragma unroll
;         for (int n = 0; n < 2; ++n)
; #pragma unroll
;           for (int m = 0; m < 4; m += 2) {
;             const int tk = pb * 256 + bj * 128 + e_wc * 32 + n * 16 + e_fr;
;             const int fi = pa * 256 + ai * 128 + e_wr * 64 + (m + (e_fq & 1)) * 16 + (e_fq >> 1) * 8;
;             f32x4* d = reinterpret_cast<f32x4*>(out + (long)tk * DM + fi);
;             const f32x4* sp = xp ? reinterpret_cast<const f32x4*>((tk < 16384 ? xp + (long)tk * DM : xs + (long)(tk - 16384) * DM) + fi) : d;
;             f32x4 o0 = sp[0], o1 = sp[1];
;             const f32x4 va = acc[ai][bj][m][n], vb2 = acc[ai][bj][m + 1][n];
; #pragma unroll
;             for (int e = 0; e < 4; ++e) { auto rr = __builtin_amdgcn_permlane16_swap(__float_as_uint(va[e]), __float_as_uint(vb2[e]), false, false);
;               o0[e] += __uint_as_float(rr[0]); o1[e] += __uint_as_float(rr[1]); }
;             d[0] = o0; d[1] = o1; }
;         SCHEDB(); } });
	v_pk_add_f32 v[110:111], v[214:215], v[110:111]
	v_pk_add_f32 v[106:107], v[218:219], v[106:107]
	v_pk_add_f32 v[104:105], v[216:217], v[104:105]
	v_pk_add_f32 v[108:109], v[212:213], v[108:109]
	global_store_dwordx4 v[244:245], v[104:107], off
	global_store_dwordx4 v[244:245], v[108:111], off offset:16
	global_load_dwordx4 v[212:215], v[244:245], off offset:528
	global_load_dwordx4 v[216:219], v[244:245], off offset:512
	s_waitcnt vmcnt(20)
	v_pk_add_f32 v[98:99], v[222:223], v[98:99]
	v_pk_add_f32 v[102:103], v[226:227], v[102:103]
	v_pk_add_f32 v[100:101], v[224:225], v[100:101]
	v_pk_add_f32 v[96:97], v[220:221], v[96:97]
	global_store_dwordx4 v[244:245], v[100:103], off offset:128
	global_store_dwordx4 v[244:245], v[96:99], off offset:144
	global_load_dwordx4 v[220:223], v[244:245], off offset:656
	global_load_dwordx4 v[224:227], v[244:245], off offset:640
	s_waitcnt vmcnt(22)
	v_pk_add_f32 v[94:95], v[230:231], v[94:95]
	v_pk_add_f32 v[90:91], v[234:235], v[90:91]
	v_pk_add_f32 v[88:89], v[232:233], v[88:89]
	v_pk_add_f32 v[92:93], v[228:229], v[92:93]
	global_store_dwordx4 v[246:247], v[88:91], off
	global_store_dwordx4 v[246:247], v[92:95], off offset:16
	global_load_dwordx4 v[228:231], v[246:247], off offset:528
	global_load_dwordx4 v[232:235], v[246:247], off offset:512
	s_waitcnt vmcnt(24)
	v_pk_add_f32 v[86:87], v[238:239], v[86:87]
	v_pk_add_f32 v[82:83], v[242:243], v[82:83]
	v_pk_add_f32 v[80:81], v[240:241], v[80:81]
	v_pk_add_f32 v[84:85], v[236:237], v[84:85]
	global_store_dwordx4 v[246:247], v[80:83], off offset:128
	global_store_dwordx4 v[246:247], v[84:87], off offset:144
	global_load_dwordx4 v[236:239], v[246:247], off offset:656
	global_load_dwordx4 v[240:243], v[246:247], off offset:640
	s_waitcnt vmcnt(26)
	v_pk_add_f32 v[78:79], v[176:177], v[78:79]
	v_pk_add_f32 v[74:75], v[180:181], v[74:75]
	v_pk_add_f32 v[72:73], v[178:179], v[72:73]
	v_pk_add_f32 v[76:77], v[174:175], v[76:77]
	global_store_dwordx4 v[248:249], v[72:75], off
	global_store_dwordx4 v[248:249], v[76:79], off offset:16
	global_load_dwordx4 v[174:177], v[248:249], off offset:528
	global_load_dwordx4 v[178:181], v[248:249], off offset:512
	s_waitcnt vmcnt(28)
	v_pk_add_f32 v[66:67], v[184:185], v[66:67]
	v_pk_add_f32 v[70:71], v[188:189], v[70:71]
	v_pk_add_f32 v[68:69], v[186:187], v[68:69]
	v_pk_add_f32 v[64:65], v[182:183], v[64:65]
	global_store_dwordx4 v[248:249], v[68:71], off offset:128
	global_store_dwordx4 v[248:249], v[64:67], off offset:144
	global_load_dwordx4 v[182:185], v[248:249], off offset:656
	global_load_dwordx4 v[186:189], v[248:249], off offset:640
	s_waitcnt vmcnt(28)
	v_pk_add_f32 v[62:63], v[198:199], v[62:63]
	v_pk_add_f32 v[58:59], v[202:203], v[58:59]
	v_pk_add_f32 v[56:57], v[200:201], v[56:57]
	v_pk_add_f32 v[60:61], v[196:197], v[60:61]
	global_store_dwordx4 v[128:129], v[56:59], off offset:512
	global_store_dwordx4 v[128:129], v[60:63], off offset:528
	s_waitcnt vmcnt(26)
	v_pk_add_f32 v[54:55], v[206:207], v[54:55]
	v_pk_add_f32 v[50:51], v[210:211], v[50:51]
	v_pk_add_f32 v[48:49], v[208:209], v[48:49]
	v_pk_add_f32 v[52:53], v[204:205], v[52:53]
	global_store_dwordx4 v[128:129], v[48:51], off offset:640
	global_store_dwordx4 v[128:129], v[52:55], off offset:656
	s_waitcnt vmcnt(24)
	v_pk_add_f32 v[46:47], v[214:215], v[46:47]
	v_pk_add_f32 v[42:43], v[218:219], v[42:43]
	v_pk_add_f32 v[40:41], v[216:217], v[40:41]
	v_pk_add_f32 v[44:45], v[212:213], v[44:45]
	global_store_dwordx4 v[244:245], v[40:43], off offset:512
	global_store_dwordx4 v[244:245], v[44:47], off offset:528
	s_waitcnt vmcnt(22)
	v_pk_add_f32 v[34:35], v[222:223], v[34:35]
	v_pk_add_f32 v[38:39], v[226:227], v[38:39]
	v_pk_add_f32 v[36:37], v[224:225], v[36:37]
	v_pk_add_f32 v[32:33], v[220:221], v[32:33]
	global_store_dwordx4 v[244:245], v[36:39], off offset:640
	global_store_dwordx4 v[244:245], v[32:35], off offset:656
	s_waitcnt vmcnt(20)
	v_pk_add_f32 v[30:31], v[230:231], v[30:31]
	v_pk_add_f32 v[26:27], v[234:235], v[26:27]
	v_pk_add_f32 v[24:25], v[232:233], v[24:25]
	v_pk_add_f32 v[28:29], v[228:229], v[28:29]
	global_store_dwordx4 v[246:247], v[24:27], off offset:512
	global_store_dwordx4 v[246:247], v[28:31], off offset:528
	s_waitcnt vmcnt(18)
	v_pk_add_f32 v[22:23], v[238:239], v[22:23]
	v_pk_add_f32 v[18:19], v[242:243], v[18:19]
	v_pk_add_f32 v[16:17], v[240:241], v[16:17]
	v_pk_add_f32 v[20:21], v[236:237], v[20:21]
	global_store_dwordx4 v[246:247], v[16:19], off offset:640
	global_store_dwordx4 v[246:247], v[20:23], off offset:656
	s_waitcnt vmcnt(16)
	v_pk_add_f32 v[14:15], v[176:177], v[14:15]
	v_pk_add_f32 v[10:11], v[180:181], v[10:11]
	v_pk_add_f32 v[8:9], v[178:179], v[8:9]
	v_pk_add_f32 v[12:13], v[174:175], v[12:13]
	global_store_dwordx4 v[248:249], v[8:11], off offset:512
	global_store_dwordx4 v[248:249], v[12:15], off offset:528
	s_waitcnt vmcnt(14)
	v_pk_add_f32 v[2:3], v[184:185], v[2:3]
	v_pk_add_f32 v[6:7], v[188:189], v[6:7]
	v_pk_add_f32 v[4:5], v[186:187], v[4:5]
	v_pk_add_f32 v[0:1], v[182:183], v[0:1]
	global_store_dwordx4 v[248:249], v[4:7], off offset:640
	global_store_dwordx4 v[248:249], v[0:3], off offset:656
	s_and_b64 vcc, exec, s[8:9]
	s_mov_b32 s11, s72
	s_mov_b32 s2, s69
	s_cbranch_vccnz .LBB0_387
